# same as previous (prep relocation + mod_partials readlane) with grid!=256 fallback to the original w_in_odd path
# speedup vs baseline: 1.0042x; 1.0042x over previous
.LBB0_890:
	s_cmp_gt_i32 s2, 63
	s_cselect_b64 s[0:1], -1, 0
	s_sub_i32 s3, s2, 32
	s_add_u32 s14, s24, 0xa10000
	s_addc_u32 s15, s25, 0
	v_readlane_b32 s4, v254, 11
	s_add_u32 s8, s24, 0x1210000
	v_readlane_b32 s5, v254, 12
	s_addc_u32 s9, s25, 0
	s_and_b64 s[0:1], s[0:1], s[4:5]
	s_cmpk_gt_u32 s2, 0xdf
	v_readlane_b32 s4, v254, 35
	s_cselect_b32 s10, s4, -1
	s_add_u32 s6, s24, 0x810000
	v_readlane_b32 s94, v254, 22
	s_addc_u32 s7, s25, 0
	v_readlane_b32 s95, v254, 23
	s_and_b64 s[4:5], s[94:95], exec
	v_readlane_b32 s4, v254, 26
	v_readlane_b32 s5, v254, 27
	s_cselect_b32 s3, s3, s10
	s_and_b64 s[4:5], s[4:5], exec
	s_cselect_b32 s3, s3, -1
	s_and_b64 s[0:1], s[0:1], exec
	v_readlane_b32 s90, v254, 13
	s_cselect_b32 s3, s3, s2
	v_readlane_b32 s91, v254, 14
	v_readlane_b32 s92, v254, 15
	s_cmp_lt_i32 s3, 0
	v_readlane_b32 s93, v254, 16
	v_readlane_b32 s91, v254, 17
	v_readlane_b32 s88, v254, 38
	v_readlane_b32 s89, v254, 39
	s_cbranch_scc1 .LBB0_935
	v_readlane_b32 s0, v254, 11
	v_readlane_b32 s1, v254, 12
	s_and_b64 s[0:1], s[0:1], exec
	s_cselect_b32 s10, 0xc0, s26
	s_lshl_b32 s11, s10, 1
	s_cmpk_gt_u32 s3, 0x1ff
	s_cbranch_scc1 .LBB0_898
	s_cmp_eq_u32 s26, 0x100
	s_cbranch_scc1 .LBB0_898
	s_lshl_b32 s12, s3, 1
	s_lshl_b32 s13, s3, 7
	s_lshl_b32 s16, s11, 6
	v_mov_b32_e32 v1, 0
	s_movk_i32 s17, 0xffc0
	s_mov_b32 s19, 0x80000
	s_movk_i32 s28, 0x104
	s_movk_i32 s29, 0x1000
	s_movk_i32 s35, 0x800
	s_branch .LBB0_894

.Lprep_in_odd:
	s_cmp_lg_u32 s26, 0x100
	s_cbranch_scc1 .LBB0_1071
	s_waitcnt vmcnt(0)
	s_add_i32 s0, s2, 0xffffff40
	s_lshl_b32 s42, s0, 1
	s_lshl_b32 s43, s0, 7
	s_add_u32 s46, s24, 0xa10000
	s_addc_u32 s47, s25, 0
	v_mov_b32_e32 v1, 0
	s_movk_i32 s17, 0xffc0
	s_mov_b32 s19, 0x80000
	s_movk_i32 s28, 0x104
	s_movk_i32 s29, 0x1000
	s_movk_i32 s35, 0x800
	s_branch .Lpi_loop
